# step16: + phase0 adaLN weight loads batched 16-deep, setup loop unrolled/batched, transpose tile loads batched
# speedup vs baseline: 1.0309x; 1.0137x over previous
.LBB0_26:
	v_and_b32_e32 v4, 0x3fc, v3
	v_cmp_gt_u32_e32 vcc, s3, v10
	v_lshlrev_b32_e32 v4, 2, v4
	v_add_u32_e32 v3, 0x800, v3
	v_cndmask_b32_e32 v13, v7, v9, vcc
	v_cndmask_b32_e32 v12, v6, v8, vcc
	v_lshl_add_u64 v[12:13], v[12:13], 0, v[4:5]
	global_load_dwordx4 v[64:67], v[12:13], off
	v_add_u32_e32 v10, 0x200, v10
	v_lshl_add_u64 v[6:7], v[6:7], 0, s[6:7]
	v_lshl_add_u64 v[8:9], v[8:9], 0, s[6:7]
	v_and_b32_e32 v4, 0x3fc, v3
	v_cmp_gt_u32_e32 vcc, s3, v10
	v_lshlrev_b32_e32 v4, 2, v4
	v_add_u32_e32 v3, 0x800, v3
	v_cndmask_b32_e32 v13, v7, v9, vcc
	v_cndmask_b32_e32 v12, v6, v8, vcc
	v_lshl_add_u64 v[12:13], v[12:13], 0, v[4:5]
	global_load_dwordx4 v[68:71], v[12:13], off
	v_add_u32_e32 v10, 0x200, v10
	v_lshl_add_u64 v[6:7], v[6:7], 0, s[6:7]
	v_lshl_add_u64 v[8:9], v[8:9], 0, s[6:7]
	v_and_b32_e32 v4, 0x3fc, v3
	v_cmp_gt_u32_e32 vcc, s3, v10
	v_lshlrev_b32_e32 v4, 2, v4
	v_add_u32_e32 v3, 0x800, v3
	v_cndmask_b32_e32 v13, v7, v9, vcc
	v_cndmask_b32_e32 v12, v6, v8, vcc
	v_lshl_add_u64 v[12:13], v[12:13], 0, v[4:5]
	global_load_dwordx4 v[72:75], v[12:13], off
	v_add_u32_e32 v10, 0x200, v10
	v_lshl_add_u64 v[6:7], v[6:7], 0, s[6:7]
	v_lshl_add_u64 v[8:9], v[8:9], 0, s[6:7]
	v_and_b32_e32 v4, 0x3fc, v3
	v_cmp_gt_u32_e32 vcc, s3, v10
	v_lshlrev_b32_e32 v4, 2, v4
	v_add_u32_e32 v3, 0x800, v3
	v_cndmask_b32_e32 v13, v7, v9, vcc
	v_cndmask_b32_e32 v12, v6, v8, vcc
	v_lshl_add_u64 v[12:13], v[12:13], 0, v[4:5]
	global_load_dwordx4 v[76:79], v[12:13], off
	v_add_u32_e32 v10, 0x200, v10
	v_lshl_add_u64 v[6:7], v[6:7], 0, s[6:7]
	v_lshl_add_u64 v[8:9], v[8:9], 0, s[6:7]
	v_and_b32_e32 v4, 0x3fc, v3
	v_cmp_gt_u32_e32 vcc, s3, v10
	v_lshlrev_b32_e32 v4, 2, v4
	v_add_u32_e32 v3, 0x800, v3
	v_cndmask_b32_e32 v13, v7, v9, vcc
	v_cndmask_b32_e32 v12, v6, v8, vcc
	v_lshl_add_u64 v[12:13], v[12:13], 0, v[4:5]
	global_load_dwordx4 v[80:83], v[12:13], off
	v_add_u32_e32 v10, 0x200, v10
	v_lshl_add_u64 v[6:7], v[6:7], 0, s[6:7]
	v_lshl_add_u64 v[8:9], v[8:9], 0, s[6:7]
	v_and_b32_e32 v4, 0x3fc, v3
	v_cmp_gt_u32_e32 vcc, s3, v10
	v_lshlrev_b32_e32 v4, 2, v4
	v_add_u32_e32 v3, 0x800, v3
	v_cndmask_b32_e32 v13, v7, v9, vcc
	v_cndmask_b32_e32 v12, v6, v8, vcc
	v_lshl_add_u64 v[12:13], v[12:13], 0, v[4:5]
	global_load_dwordx4 v[84:87], v[12:13], off
	v_add_u32_e32 v10, 0x200, v10
	v_lshl_add_u64 v[6:7], v[6:7], 0, s[6:7]
	v_lshl_add_u64 v[8:9], v[8:9], 0, s[6:7]
	v_and_b32_e32 v4, 0x3fc, v3
	v_cmp_gt_u32_e32 vcc, s3, v10
	v_lshlrev_b32_e32 v4, 2, v4
	v_add_u32_e32 v3, 0x800, v3
	v_cndmask_b32_e32 v13, v7, v9, vcc
	v_cndmask_b32_e32 v12, v6, v8, vcc
	v_lshl_add_u64 v[12:13], v[12:13], 0, v[4:5]
	global_load_dwordx4 v[88:91], v[12:13], off
	v_add_u32_e32 v10, 0x200, v10
	v_lshl_add_u64 v[6:7], v[6:7], 0, s[6:7]
	v_lshl_add_u64 v[8:9], v[8:9], 0, s[6:7]
	v_and_b32_e32 v4, 0x3fc, v3
	v_cmp_gt_u32_e32 vcc, s3, v10
	v_lshlrev_b32_e32 v4, 2, v4
	v_add_u32_e32 v3, 0x800, v3
	v_cndmask_b32_e32 v13, v7, v9, vcc
	v_cndmask_b32_e32 v12, v6, v8, vcc
	v_lshl_add_u64 v[12:13], v[12:13], 0, v[4:5]
	global_load_dwordx4 v[92:95], v[12:13], off
	v_add_u32_e32 v10, 0x200, v10
	v_lshl_add_u64 v[6:7], v[6:7], 0, s[6:7]
	v_lshl_add_u64 v[8:9], v[8:9], 0, s[6:7]
	v_and_b32_e32 v4, 0x3fc, v3
	v_cmp_gt_u32_e32 vcc, s3, v10
	v_lshlrev_b32_e32 v4, 2, v4
	v_add_u32_e32 v3, 0x800, v3
	v_cndmask_b32_e32 v13, v7, v9, vcc
	v_cndmask_b32_e32 v12, v6, v8, vcc
	v_lshl_add_u64 v[12:13], v[12:13], 0, v[4:5]
	global_load_dwordx4 v[96:99], v[12:13], off
	v_add_u32_e32 v10, 0x200, v10
	v_lshl_add_u64 v[6:7], v[6:7], 0, s[6:7]
	v_lshl_add_u64 v[8:9], v[8:9], 0, s[6:7]
	v_and_b32_e32 v4, 0x3fc, v3
	v_cmp_gt_u32_e32 vcc, s3, v10
	v_lshlrev_b32_e32 v4, 2, v4
	v_add_u32_e32 v3, 0x800, v3
	v_cndmask_b32_e32 v13, v7, v9, vcc
	v_cndmask_b32_e32 v12, v6, v8, vcc
	v_lshl_add_u64 v[12:13], v[12:13], 0, v[4:5]
	global_load_dwordx4 v[100:103], v[12:13], off
	v_add_u32_e32 v10, 0x200, v10
	v_lshl_add_u64 v[6:7], v[6:7], 0, s[6:7]
	v_lshl_add_u64 v[8:9], v[8:9], 0, s[6:7]
	v_and_b32_e32 v4, 0x3fc, v3
	v_cmp_gt_u32_e32 vcc, s3, v10
	v_lshlrev_b32_e32 v4, 2, v4
	v_add_u32_e32 v3, 0x800, v3
	v_cndmask_b32_e32 v13, v7, v9, vcc
	v_cndmask_b32_e32 v12, v6, v8, vcc
	v_lshl_add_u64 v[12:13], v[12:13], 0, v[4:5]
	global_load_dwordx4 v[104:107], v[12:13], off
	v_add_u32_e32 v10, 0x200, v10
	v_lshl_add_u64 v[6:7], v[6:7], 0, s[6:7]
	v_lshl_add_u64 v[8:9], v[8:9], 0, s[6:7]
	v_and_b32_e32 v4, 0x3fc, v3
	v_cmp_gt_u32_e32 vcc, s3, v10
	v_lshlrev_b32_e32 v4, 2, v4
	v_add_u32_e32 v3, 0x800, v3
	v_cndmask_b32_e32 v13, v7, v9, vcc
	v_cndmask_b32_e32 v12, v6, v8, vcc
	v_lshl_add_u64 v[12:13], v[12:13], 0, v[4:5]
	global_load_dwordx4 v[108:111], v[12:13], off
	v_add_u32_e32 v10, 0x200, v10
	v_lshl_add_u64 v[6:7], v[6:7], 0, s[6:7]
	v_lshl_add_u64 v[8:9], v[8:9], 0, s[6:7]
	s_waitcnt vmcnt(11)
	ds_write_b128 v1, v[64:67]
	v_add_u32_e32 v1, 0x2000, v1
	s_waitcnt vmcnt(10)
	ds_write_b128 v1, v[68:71]
	v_add_u32_e32 v1, 0x2000, v1
	s_waitcnt vmcnt(9)
	ds_write_b128 v1, v[72:75]
	v_add_u32_e32 v1, 0x2000, v1
	s_waitcnt vmcnt(8)
	ds_write_b128 v1, v[76:79]
	v_add_u32_e32 v1, 0x2000, v1
	s_waitcnt vmcnt(7)
	ds_write_b128 v1, v[80:83]
	v_add_u32_e32 v1, 0x2000, v1
	s_waitcnt vmcnt(6)
	ds_write_b128 v1, v[84:87]
	v_add_u32_e32 v1, 0x2000, v1
	s_waitcnt vmcnt(5)
	ds_write_b128 v1, v[88:91]
	v_add_u32_e32 v1, 0x2000, v1
	s_waitcnt vmcnt(4)
	ds_write_b128 v1, v[92:95]
	v_add_u32_e32 v1, 0x2000, v1
	s_waitcnt vmcnt(3)
	ds_write_b128 v1, v[96:99]
	v_add_u32_e32 v1, 0x2000, v1
	s_waitcnt vmcnt(2)
	ds_write_b128 v1, v[100:103]
	v_add_u32_e32 v1, 0x2000, v1
	s_waitcnt vmcnt(1)
	ds_write_b128 v1, v[104:107]
	v_add_u32_e32 v1, 0x2000, v1
	s_waitcnt vmcnt(0)
	ds_write_b128 v1, v[108:111]
	v_add_u32_e32 v1, 0x2000, v1
	s_or_b64 exec, exec, s[4:5]
	v_and_b32_e32 v1, 63, v2
	v_lshrrev_b32_e32 v5, 6, v2
	s_mov_b32 s3, 0x180000
	v_lshrrev_b32_e32 v4, 6, v2
	v_lshlrev_b32_e32 v10, 2, v1
	v_mad_u64_u32 v[6:7], s[4:5], v5, s3, 0
	v_mov_b32_e32 v11, 0
	v_or_b32_e32 v12, 0x18000, v10
	v_mul_u32_u24_e32 v13, 0x1800, v4
	v_or_b32_e32 v6, v6, v10
	v_lshl_add_u64 v[8:9], s[86:87], 0, v[10:11]
	s_mov_b64 s[4:5], 0x3b700000
	v_lshl_or_b32 v10, v4, 8, v10
	v_lshlrev_b32_e32 v3, 9, v4
	v_add_u32_e32 v5, 0xfffffe00, v2
	v_lshl_add_u64 v[8:9], v[8:9], 0, s[4:5]
	v_add_u32_e32 v15, 0x18000, v10
	s_mov_b64 s[4:5], 0x3000
	v_add_u32_e32 v16, v12, v13
	s_movk_i32 s3, 0x3000
	s_mov_b64 s[6:7], 0x18000
	s_movk_i32 s88, 0x3ff
	s_mov_b32 s89, s2
	s_waitcnt lgkmcnt(0)
	s_barrier

.LBB0_29:
	global_load_dword v64, v[10:11], off
	v_lshl_add_u64 v[10:11], v[10:11], 0, s[4:5]
	global_load_dword v65, v[10:11], off
	v_lshl_add_u64 v[10:11], v[10:11], 0, s[4:5]
	global_load_dword v66, v[10:11], off
	v_lshl_add_u64 v[10:11], v[10:11], 0, s[4:5]
	global_load_dword v67, v[10:11], off
	v_lshl_add_u64 v[10:11], v[10:11], 0, s[4:5]
	global_load_dword v68, v[10:11], off
	v_lshl_add_u64 v[10:11], v[10:11], 0, s[4:5]
	global_load_dword v69, v[10:11], off
	v_lshl_add_u64 v[10:11], v[10:11], 0, s[4:5]
	global_load_dword v70, v[10:11], off
	v_lshl_add_u64 v[10:11], v[10:11], 0, s[4:5]
	global_load_dword v71, v[10:11], off
	v_lshl_add_u64 v[10:11], v[10:11], 0, s[4:5]
	global_load_dword v72, v[10:11], off
	v_lshl_add_u64 v[10:11], v[10:11], 0, s[4:5]
	global_load_dword v73, v[10:11], off
	v_lshl_add_u64 v[10:11], v[10:11], 0, s[4:5]
	global_load_dword v74, v[10:11], off
	v_lshl_add_u64 v[10:11], v[10:11], 0, s[4:5]
	global_load_dword v75, v[10:11], off
	v_lshl_add_u64 v[10:11], v[10:11], 0, s[4:5]
	global_load_dword v76, v[10:11], off
	v_lshl_add_u64 v[10:11], v[10:11], 0, s[4:5]
	global_load_dword v77, v[10:11], off
	v_lshl_add_u64 v[10:11], v[10:11], 0, s[4:5]
	global_load_dword v78, v[10:11], off
	v_lshl_add_u64 v[10:11], v[10:11], 0, s[4:5]
	global_load_dword v79, v[10:11], off
	v_lshl_add_u64 v[10:11], v[10:11], 0, s[4:5]
	v_add_u32_e32 v56, s23, v3
	ds_read2st64_b32 v[40:41], v56 offset1:16
	ds_read2st64_b32 v[42:43], v56 offset0:32 offset1:48
	ds_read2st64_b32 v[44:45], v56 offset0:64 offset1:80
	ds_read2st64_b32 v[46:47], v56 offset0:96 offset1:112
	ds_read2st64_b32 v[48:49], v56 offset0:128 offset1:144
	ds_read2st64_b32 v[50:51], v56 offset0:160 offset1:176
	ds_read2st64_b32 v[52:53], v56 offset0:192 offset1:208
	ds_read2st64_b32 v[54:55], v56 offset0:224 offset1:240
	v_add_u32_e32 v57, 0x10000, v56
	v_add_u32_e32 v58, 0x11000, v56
	v_add_u32_e32 v59, 0x12000, v56
	v_add_u32_e32 v60, 0x13000, v56
	v_add_u32_e32 v61, 0x14000, v56
	v_add_u32_e32 v62, 0x15000, v56
	v_add_u32_e32 v63, 0x16000, v56
	v_add_u32_e32 v56, 0x17000, v56
	ds_read_b32 v57, v57
	ds_read_b32 v58, v58
	ds_read_b32 v59, v59
	ds_read_b32 v60, v60
	ds_read_b32 v61, v61
	ds_read_b32 v62, v62
	ds_read_b32 v63, v63
	ds_read_b32 v56, v56
	s_add_i32 s23, s23, 4
	s_waitcnt vmcnt(15) lgkmcnt(14)
	v_fmac_f32_e32 v12, v64, v40
	v_fmac_f32_e32 v13, v64, v41
	v_fmac_f32_e32 v17, v64, v42
	v_fmac_f32_e32 v18, v64, v43
	s_waitcnt lgkmcnt(13)
	v_fmac_f32_e32 v19, v64, v44
	v_fmac_f32_e32 v20, v64, v45
	s_waitcnt lgkmcnt(12)
	v_fmac_f32_e32 v21, v64, v46
	v_fmac_f32_e32 v22, v64, v47
	s_waitcnt lgkmcnt(11)
	v_fmac_f32_e32 v23, v64, v48
	v_fmac_f32_e32 v24, v64, v49
	s_waitcnt lgkmcnt(10)
	v_fmac_f32_e32 v25, v64, v50
	v_fmac_f32_e32 v26, v64, v51
	s_waitcnt lgkmcnt(9)
	v_fmac_f32_e32 v27, v64, v52
	v_fmac_f32_e32 v28, v64, v53
	s_waitcnt lgkmcnt(8)
	v_fmac_f32_e32 v29, v64, v54
	v_fmac_f32_e32 v30, v64, v55
	s_waitcnt lgkmcnt(7)
	v_fmac_f32_e32 v31, v64, v57
	s_waitcnt lgkmcnt(6)
	v_fmac_f32_e32 v32, v64, v58
	s_waitcnt lgkmcnt(5)
	v_fmac_f32_e32 v33, v64, v59
	s_waitcnt lgkmcnt(4)
	v_fmac_f32_e32 v34, v64, v60
	s_waitcnt lgkmcnt(3)
	v_fmac_f32_e32 v35, v64, v61
	s_waitcnt lgkmcnt(2)
	v_fmac_f32_e32 v36, v64, v62
	s_waitcnt lgkmcnt(1)
	v_fmac_f32_e32 v37, v64, v63
	s_waitcnt lgkmcnt(0)
	v_fmac_f32_e32 v38, v64, v56
	v_add_u32_e32 v56, s23, v3
	ds_read2st64_b32 v[40:41], v56 offset1:16
	ds_read2st64_b32 v[42:43], v56 offset0:32 offset1:48
	ds_read2st64_b32 v[44:45], v56 offset0:64 offset1:80
	ds_read2st64_b32 v[46:47], v56 offset0:96 offset1:112
	ds_read2st64_b32 v[48:49], v56 offset0:128 offset1:144
	ds_read2st64_b32 v[50:51], v56 offset0:160 offset1:176
	ds_read2st64_b32 v[52:53], v56 offset0:192 offset1:208
	ds_read2st64_b32 v[54:55], v56 offset0:224 offset1:240
	v_add_u32_e32 v57, 0x10000, v56
	v_add_u32_e32 v58, 0x11000, v56
	v_add_u32_e32 v59, 0x12000, v56
	v_add_u32_e32 v60, 0x13000, v56
	v_add_u32_e32 v61, 0x14000, v56
	v_add_u32_e32 v62, 0x15000, v56
	v_add_u32_e32 v63, 0x16000, v56
	v_add_u32_e32 v56, 0x17000, v56
	ds_read_b32 v57, v57
	ds_read_b32 v58, v58
	ds_read_b32 v59, v59
	ds_read_b32 v60, v60
	ds_read_b32 v61, v61
	ds_read_b32 v62, v62
	ds_read_b32 v63, v63
	ds_read_b32 v56, v56
	s_add_i32 s23, s23, 4
	s_waitcnt vmcnt(14) lgkmcnt(14)
	v_fmac_f32_e32 v12, v65, v40
	v_fmac_f32_e32 v13, v65, v41
	v_fmac_f32_e32 v17, v65, v42
	v_fmac_f32_e32 v18, v65, v43
	s_waitcnt lgkmcnt(13)
	v_fmac_f32_e32 v19, v65, v44
	v_fmac_f32_e32 v20, v65, v45
	s_waitcnt lgkmcnt(12)
	v_fmac_f32_e32 v21, v65, v46
	v_fmac_f32_e32 v22, v65, v47
	s_waitcnt lgkmcnt(11)
	v_fmac_f32_e32 v23, v65, v48
	v_fmac_f32_e32 v24, v65, v49
	s_waitcnt lgkmcnt(10)
	v_fmac_f32_e32 v25, v65, v50
	v_fmac_f32_e32 v26, v65, v51
	s_waitcnt lgkmcnt(9)
	v_fmac_f32_e32 v27, v65, v52
	v_fmac_f32_e32 v28, v65, v53
	s_waitcnt lgkmcnt(8)
	v_fmac_f32_e32 v29, v65, v54
	v_fmac_f32_e32 v30, v65, v55
	s_waitcnt lgkmcnt(7)
	v_fmac_f32_e32 v31, v65, v57
	s_waitcnt lgkmcnt(6)
	v_fmac_f32_e32 v32, v65, v58
	s_waitcnt lgkmcnt(5)
	v_fmac_f32_e32 v33, v65, v59
	s_waitcnt lgkmcnt(4)
	v_fmac_f32_e32 v34, v65, v60
	s_waitcnt lgkmcnt(3)
	v_fmac_f32_e32 v35, v65, v61
	s_waitcnt lgkmcnt(2)
	v_fmac_f32_e32 v36, v65, v62
	s_waitcnt lgkmcnt(1)
	v_fmac_f32_e32 v37, v65, v63
	s_waitcnt lgkmcnt(0)
	v_fmac_f32_e32 v38, v65, v56
	v_add_u32_e32 v56, s23, v3
	ds_read2st64_b32 v[40:41], v56 offset1:16
	ds_read2st64_b32 v[42:43], v56 offset0:32 offset1:48
	ds_read2st64_b32 v[44:45], v56 offset0:64 offset1:80
	ds_read2st64_b32 v[46:47], v56 offset0:96 offset1:112
	ds_read2st64_b32 v[48:49], v56 offset0:128 offset1:144
	ds_read2st64_b32 v[50:51], v56 offset0:160 offset1:176
	ds_read2st64_b32 v[52:53], v56 offset0:192 offset1:208
	ds_read2st64_b32 v[54:55], v56 offset0:224 offset1:240
	v_add_u32_e32 v57, 0x10000, v56
	v_add_u32_e32 v58, 0x11000, v56
	v_add_u32_e32 v59, 0x12000, v56
	v_add_u32_e32 v60, 0x13000, v56
	v_add_u32_e32 v61, 0x14000, v56
	v_add_u32_e32 v62, 0x15000, v56
	v_add_u32_e32 v63, 0x16000, v56
	v_add_u32_e32 v56, 0x17000, v56
	ds_read_b32 v57, v57
	ds_read_b32 v58, v58
	ds_read_b32 v59, v59
	ds_read_b32 v60, v60
	ds_read_b32 v61, v61
	ds_read_b32 v62, v62
	ds_read_b32 v63, v63
	ds_read_b32 v56, v56
	s_add_i32 s23, s23, 4
	s_waitcnt vmcnt(13) lgkmcnt(14)
	v_fmac_f32_e32 v12, v66, v40
	v_fmac_f32_e32 v13, v66, v41
	v_fmac_f32_e32 v17, v66, v42
	v_fmac_f32_e32 v18, v66, v43
	s_waitcnt lgkmcnt(13)
	v_fmac_f32_e32 v19, v66, v44
	v_fmac_f32_e32 v20, v66, v45
	s_waitcnt lgkmcnt(12)
	v_fmac_f32_e32 v21, v66, v46
	v_fmac_f32_e32 v22, v66, v47
	s_waitcnt lgkmcnt(11)
	v_fmac_f32_e32 v23, v66, v48
	v_fmac_f32_e32 v24, v66, v49
	s_waitcnt lgkmcnt(10)
	v_fmac_f32_e32 v25, v66, v50
	v_fmac_f32_e32 v26, v66, v51
	s_waitcnt lgkmcnt(9)
	v_fmac_f32_e32 v27, v66, v52
	v_fmac_f32_e32 v28, v66, v53
	s_waitcnt lgkmcnt(8)
	v_fmac_f32_e32 v29, v66, v54
	v_fmac_f32_e32 v30, v66, v55
	s_waitcnt lgkmcnt(7)
	v_fmac_f32_e32 v31, v66, v57
	s_waitcnt lgkmcnt(6)
	v_fmac_f32_e32 v32, v66, v58
	s_waitcnt lgkmcnt(5)
	v_fmac_f32_e32 v33, v66, v59
	s_waitcnt lgkmcnt(4)
	v_fmac_f32_e32 v34, v66, v60
	s_waitcnt lgkmcnt(3)
	v_fmac_f32_e32 v35, v66, v61
	s_waitcnt lgkmcnt(2)
	v_fmac_f32_e32 v36, v66, v62
	s_waitcnt lgkmcnt(1)
	v_fmac_f32_e32 v37, v66, v63
	s_waitcnt lgkmcnt(0)
	v_fmac_f32_e32 v38, v66, v56
	v_add_u32_e32 v56, s23, v3
	ds_read2st64_b32 v[40:41], v56 offset1:16
	ds_read2st64_b32 v[42:43], v56 offset0:32 offset1:48
	ds_read2st64_b32 v[44:45], v56 offset0:64 offset1:80
	ds_read2st64_b32 v[46:47], v56 offset0:96 offset1:112
	ds_read2st64_b32 v[48:49], v56 offset0:128 offset1:144
	ds_read2st64_b32 v[50:51], v56 offset0:160 offset1:176
	ds_read2st64_b32 v[52:53], v56 offset0:192 offset1:208
	ds_read2st64_b32 v[54:55], v56 offset0:224 offset1:240
	v_add_u32_e32 v57, 0x10000, v56
	v_add_u32_e32 v58, 0x11000, v56
	v_add_u32_e32 v59, 0x12000, v56
	v_add_u32_e32 v60, 0x13000, v56
	v_add_u32_e32 v61, 0x14000, v56
	v_add_u32_e32 v62, 0x15000, v56
	v_add_u32_e32 v63, 0x16000, v56
	v_add_u32_e32 v56, 0x17000, v56
	ds_read_b32 v57, v57
	ds_read_b32 v58, v58
	ds_read_b32 v59, v59
	ds_read_b32 v60, v60
	ds_read_b32 v61, v61
	ds_read_b32 v62, v62
	ds_read_b32 v63, v63
	ds_read_b32 v56, v56
	s_add_i32 s23, s23, 4
	s_waitcnt vmcnt(12) lgkmcnt(14)
	v_fmac_f32_e32 v12, v67, v40
	v_fmac_f32_e32 v13, v67, v41
	v_fmac_f32_e32 v17, v67, v42
	v_fmac_f32_e32 v18, v67, v43
	s_waitcnt lgkmcnt(13)
	v_fmac_f32_e32 v19, v67, v44
	v_fmac_f32_e32 v20, v67, v45
	s_waitcnt lgkmcnt(12)
	v_fmac_f32_e32 v21, v67, v46
	v_fmac_f32_e32 v22, v67, v47
	s_waitcnt lgkmcnt(11)
	v_fmac_f32_e32 v23, v67, v48
	v_fmac_f32_e32 v24, v67, v49
	s_waitcnt lgkmcnt(10)
	v_fmac_f32_e32 v25, v67, v50
	v_fmac_f32_e32 v26, v67, v51
	s_waitcnt lgkmcnt(9)
	v_fmac_f32_e32 v27, v67, v52
	v_fmac_f32_e32 v28, v67, v53
	s_waitcnt lgkmcnt(8)
	v_fmac_f32_e32 v29, v67, v54
	v_fmac_f32_e32 v30, v67, v55
	s_waitcnt lgkmcnt(7)
	v_fmac_f32_e32 v31, v67, v57
	s_waitcnt lgkmcnt(6)
	v_fmac_f32_e32 v32, v67, v58
	s_waitcnt lgkmcnt(5)
	v_fmac_f32_e32 v33, v67, v59
	s_waitcnt lgkmcnt(4)
	v_fmac_f32_e32 v34, v67, v60
	s_waitcnt lgkmcnt(3)
	v_fmac_f32_e32 v35, v67, v61
	s_waitcnt lgkmcnt(2)
	v_fmac_f32_e32 v36, v67, v62
	s_waitcnt lgkmcnt(1)
	v_fmac_f32_e32 v37, v67, v63
	s_waitcnt lgkmcnt(0)
	v_fmac_f32_e32 v38, v67, v56
	v_add_u32_e32 v56, s23, v3
	ds_read2st64_b32 v[40:41], v56 offset1:16
	ds_read2st64_b32 v[42:43], v56 offset0:32 offset1:48
	ds_read2st64_b32 v[44:45], v56 offset0:64 offset1:80
	ds_read2st64_b32 v[46:47], v56 offset0:96 offset1:112
	ds_read2st64_b32 v[48:49], v56 offset0:128 offset1:144
	ds_read2st64_b32 v[50:51], v56 offset0:160 offset1:176
	ds_read2st64_b32 v[52:53], v56 offset0:192 offset1:208
	ds_read2st64_b32 v[54:55], v56 offset0:224 offset1:240
	v_add_u32_e32 v57, 0x10000, v56
	v_add_u32_e32 v58, 0x11000, v56
	v_add_u32_e32 v59, 0x12000, v56
	v_add_u32_e32 v60, 0x13000, v56
	v_add_u32_e32 v61, 0x14000, v56
	v_add_u32_e32 v62, 0x15000, v56
	v_add_u32_e32 v63, 0x16000, v56
	v_add_u32_e32 v56, 0x17000, v56
	ds_read_b32 v57, v57
	ds_read_b32 v58, v58
	ds_read_b32 v59, v59
	ds_read_b32 v60, v60
	ds_read_b32 v61, v61
	ds_read_b32 v62, v62
	ds_read_b32 v63, v63
	ds_read_b32 v56, v56
	s_add_i32 s23, s23, 4
	s_waitcnt vmcnt(11) lgkmcnt(14)
	v_fmac_f32_e32 v12, v68, v40
	v_fmac_f32_e32 v13, v68, v41
	v_fmac_f32_e32 v17, v68, v42
	v_fmac_f32_e32 v18, v68, v43
	s_waitcnt lgkmcnt(13)
	v_fmac_f32_e32 v19, v68, v44
	v_fmac_f32_e32 v20, v68, v45
	s_waitcnt lgkmcnt(12)
	v_fmac_f32_e32 v21, v68, v46
	v_fmac_f32_e32 v22, v68, v47
	s_waitcnt lgkmcnt(11)
	v_fmac_f32_e32 v23, v68, v48
	v_fmac_f32_e32 v24, v68, v49
	s_waitcnt lgkmcnt(10)
	v_fmac_f32_e32 v25, v68, v50
	v_fmac_f32_e32 v26, v68, v51
	s_waitcnt lgkmcnt(9)
	v_fmac_f32_e32 v27, v68, v52
	v_fmac_f32_e32 v28, v68, v53
	s_waitcnt lgkmcnt(8)
	v_fmac_f32_e32 v29, v68, v54
	v_fmac_f32_e32 v30, v68, v55
	s_waitcnt lgkmcnt(7)
	v_fmac_f32_e32 v31, v68, v57
	s_waitcnt lgkmcnt(6)
	v_fmac_f32_e32 v32, v68, v58
	s_waitcnt lgkmcnt(5)
	v_fmac_f32_e32 v33, v68, v59
	s_waitcnt lgkmcnt(4)
	v_fmac_f32_e32 v34, v68, v60
	s_waitcnt lgkmcnt(3)
	v_fmac_f32_e32 v35, v68, v61
	s_waitcnt lgkmcnt(2)
	v_fmac_f32_e32 v36, v68, v62
	s_waitcnt lgkmcnt(1)
	v_fmac_f32_e32 v37, v68, v63
	s_waitcnt lgkmcnt(0)
	v_fmac_f32_e32 v38, v68, v56
	v_add_u32_e32 v56, s23, v3
	ds_read2st64_b32 v[40:41], v56 offset1:16
	ds_read2st64_b32 v[42:43], v56 offset0:32 offset1:48
	ds_read2st64_b32 v[44:45], v56 offset0:64 offset1:80
	ds_read2st64_b32 v[46:47], v56 offset0:96 offset1:112
	ds_read2st64_b32 v[48:49], v56 offset0:128 offset1:144
	ds_read2st64_b32 v[50:51], v56 offset0:160 offset1:176
	ds_read2st64_b32 v[52:53], v56 offset0:192 offset1:208
	ds_read2st64_b32 v[54:55], v56 offset0:224 offset1:240
	v_add_u32_e32 v57, 0x10000, v56
	v_add_u32_e32 v58, 0x11000, v56
	v_add_u32_e32 v59, 0x12000, v56
	v_add_u32_e32 v60, 0x13000, v56
	v_add_u32_e32 v61, 0x14000, v56
	v_add_u32_e32 v62, 0x15000, v56
	v_add_u32_e32 v63, 0x16000, v56
	v_add_u32_e32 v56, 0x17000, v56
	ds_read_b32 v57, v57
	ds_read_b32 v58, v58
	ds_read_b32 v59, v59
	ds_read_b32 v60, v60
	ds_read_b32 v61, v61
	ds_read_b32 v62, v62
	ds_read_b32 v63, v63
	ds_read_b32 v56, v56
	s_add_i32 s23, s23, 4
	s_waitcnt vmcnt(10) lgkmcnt(14)
	v_fmac_f32_e32 v12, v69, v40
	v_fmac_f32_e32 v13, v69, v41
	v_fmac_f32_e32 v17, v69, v42
	v_fmac_f32_e32 v18, v69, v43
	s_waitcnt lgkmcnt(13)
	v_fmac_f32_e32 v19, v69, v44
	v_fmac_f32_e32 v20, v69, v45
	s_waitcnt lgkmcnt(12)
	v_fmac_f32_e32 v21, v69, v46
	v_fmac_f32_e32 v22, v69, v47
	s_waitcnt lgkmcnt(11)
	v_fmac_f32_e32 v23, v69, v48
	v_fmac_f32_e32 v24, v69, v49
	s_waitcnt lgkmcnt(10)
	v_fmac_f32_e32 v25, v69, v50
	v_fmac_f32_e32 v26, v69, v51
	s_waitcnt lgkmcnt(9)
	v_fmac_f32_e32 v27, v69, v52
	v_fmac_f32_e32 v28, v69, v53
	s_waitcnt lgkmcnt(8)
	v_fmac_f32_e32 v29, v69, v54
	v_fmac_f32_e32 v30, v69, v55
	s_waitcnt lgkmcnt(7)
	v_fmac_f32_e32 v31, v69, v57
	s_waitcnt lgkmcnt(6)
	v_fmac_f32_e32 v32, v69, v58
	s_waitcnt lgkmcnt(5)
	v_fmac_f32_e32 v33, v69, v59
	s_waitcnt lgkmcnt(4)
	v_fmac_f32_e32 v34, v69, v60
	s_waitcnt lgkmcnt(3)
	v_fmac_f32_e32 v35, v69, v61
	s_waitcnt lgkmcnt(2)
	v_fmac_f32_e32 v36, v69, v62
	s_waitcnt lgkmcnt(1)
	v_fmac_f32_e32 v37, v69, v63
	s_waitcnt lgkmcnt(0)
	v_fmac_f32_e32 v38, v69, v56
	v_add_u32_e32 v56, s23, v3
	ds_read2st64_b32 v[40:41], v56 offset1:16
	ds_read2st64_b32 v[42:43], v56 offset0:32 offset1:48
	ds_read2st64_b32 v[44:45], v56 offset0:64 offset1:80
	ds_read2st64_b32 v[46:47], v56 offset0:96 offset1:112
	ds_read2st64_b32 v[48:49], v56 offset0:128 offset1:144
	ds_read2st64_b32 v[50:51], v56 offset0:160 offset1:176
	ds_read2st64_b32 v[52:53], v56 offset0:192 offset1:208
	ds_read2st64_b32 v[54:55], v56 offset0:224 offset1:240
	v_add_u32_e32 v57, 0x10000, v56
	v_add_u32_e32 v58, 0x11000, v56
	v_add_u32_e32 v59, 0x12000, v56
	v_add_u32_e32 v60, 0x13000, v56
	v_add_u32_e32 v61, 0x14000, v56
	v_add_u32_e32 v62, 0x15000, v56
	v_add_u32_e32 v63, 0x16000, v56
	v_add_u32_e32 v56, 0x17000, v56
	ds_read_b32 v57, v57
	ds_read_b32 v58, v58
	ds_read_b32 v59, v59
	ds_read_b32 v60, v60
	ds_read_b32 v61, v61
	ds_read_b32 v62, v62
	ds_read_b32 v63, v63
	ds_read_b32 v56, v56
	s_add_i32 s23, s23, 4
	s_waitcnt vmcnt(9) lgkmcnt(14)
	v_fmac_f32_e32 v12, v70, v40
	v_fmac_f32_e32 v13, v70, v41
	v_fmac_f32_e32 v17, v70, v42
	v_fmac_f32_e32 v18, v70, v43
	s_waitcnt lgkmcnt(13)
	v_fmac_f32_e32 v19, v70, v44
	v_fmac_f32_e32 v20, v70, v45
	s_waitcnt lgkmcnt(12)
	v_fmac_f32_e32 v21, v70, v46
	v_fmac_f32_e32 v22, v70, v47
	s_waitcnt lgkmcnt(11)
	v_fmac_f32_e32 v23, v70, v48
	v_fmac_f32_e32 v24, v70, v49
	s_waitcnt lgkmcnt(10)
	v_fmac_f32_e32 v25, v70, v50
	v_fmac_f32_e32 v26, v70, v51
	s_waitcnt lgkmcnt(9)
	v_fmac_f32_e32 v27, v70, v52
	v_fmac_f32_e32 v28, v70, v53
	s_waitcnt lgkmcnt(8)
	v_fmac_f32_e32 v29, v70, v54
	v_fmac_f32_e32 v30, v70, v55
	s_waitcnt lgkmcnt(7)
	v_fmac_f32_e32 v31, v70, v57
	s_waitcnt lgkmcnt(6)
	v_fmac_f32_e32 v32, v70, v58
	s_waitcnt lgkmcnt(5)
	v_fmac_f32_e32 v33, v70, v59
	s_waitcnt lgkmcnt(4)
	v_fmac_f32_e32 v34, v70, v60
	s_waitcnt lgkmcnt(3)
	v_fmac_f32_e32 v35, v70, v61
	s_waitcnt lgkmcnt(2)
	v_fmac_f32_e32 v36, v70, v62
	s_waitcnt lgkmcnt(1)
	v_fmac_f32_e32 v37, v70, v63
	s_waitcnt lgkmcnt(0)
	v_fmac_f32_e32 v38, v70, v56
	v_add_u32_e32 v56, s23, v3
	ds_read2st64_b32 v[40:41], v56 offset1:16
	ds_read2st64_b32 v[42:43], v56 offset0:32 offset1:48
	ds_read2st64_b32 v[44:45], v56 offset0:64 offset1:80
	ds_read2st64_b32 v[46:47], v56 offset0:96 offset1:112
	ds_read2st64_b32 v[48:49], v56 offset0:128 offset1:144
	ds_read2st64_b32 v[50:51], v56 offset0:160 offset1:176
	ds_read2st64_b32 v[52:53], v56 offset0:192 offset1:208
	ds_read2st64_b32 v[54:55], v56 offset0:224 offset1:240
	v_add_u32_e32 v57, 0x10000, v56
	v_add_u32_e32 v58, 0x11000, v56
	v_add_u32_e32 v59, 0x12000, v56
	v_add_u32_e32 v60, 0x13000, v56
	v_add_u32_e32 v61, 0x14000, v56
	v_add_u32_e32 v62, 0x15000, v56
	v_add_u32_e32 v63, 0x16000, v56
	v_add_u32_e32 v56, 0x17000, v56
	ds_read_b32 v57, v57
	ds_read_b32 v58, v58
	ds_read_b32 v59, v59
	ds_read_b32 v60, v60
	ds_read_b32 v61, v61
	ds_read_b32 v62, v62
	ds_read_b32 v63, v63
	ds_read_b32 v56, v56
	s_add_i32 s23, s23, 4
	s_waitcnt vmcnt(8) lgkmcnt(14)
	v_fmac_f32_e32 v12, v71, v40
	v_fmac_f32_e32 v13, v71, v41
	v_fmac_f32_e32 v17, v71, v42
	v_fmac_f32_e32 v18, v71, v43
	s_waitcnt lgkmcnt(13)
	v_fmac_f32_e32 v19, v71, v44
	v_fmac_f32_e32 v20, v71, v45
	s_waitcnt lgkmcnt(12)
	v_fmac_f32_e32 v21, v71, v46
	v_fmac_f32_e32 v22, v71, v47
	s_waitcnt lgkmcnt(11)
	v_fmac_f32_e32 v23, v71, v48
	v_fmac_f32_e32 v24, v71, v49
	s_waitcnt lgkmcnt(10)
	v_fmac_f32_e32 v25, v71, v50
	v_fmac_f32_e32 v26, v71, v51
	s_waitcnt lgkmcnt(9)
	v_fmac_f32_e32 v27, v71, v52
	v_fmac_f32_e32 v28, v71, v53
	s_waitcnt lgkmcnt(8)
	v_fmac_f32_e32 v29, v71, v54
	v_fmac_f32_e32 v30, v71, v55
	s_waitcnt lgkmcnt(7)
	v_fmac_f32_e32 v31, v71, v57
	s_waitcnt lgkmcnt(6)
	v_fmac_f32_e32 v32, v71, v58
	s_waitcnt lgkmcnt(5)
	v_fmac_f32_e32 v33, v71, v59
	s_waitcnt lgkmcnt(4)
	v_fmac_f32_e32 v34, v71, v60
	s_waitcnt lgkmcnt(3)
	v_fmac_f32_e32 v35, v71, v61
	s_waitcnt lgkmcnt(2)
	v_fmac_f32_e32 v36, v71, v62
	s_waitcnt lgkmcnt(1)
	v_fmac_f32_e32 v37, v71, v63
	s_waitcnt lgkmcnt(0)
	v_fmac_f32_e32 v38, v71, v56
	v_add_u32_e32 v56, s23, v3
	ds_read2st64_b32 v[40:41], v56 offset1:16
	ds_read2st64_b32 v[42:43], v56 offset0:32 offset1:48
	ds_read2st64_b32 v[44:45], v56 offset0:64 offset1:80
	ds_read2st64_b32 v[46:47], v56 offset0:96 offset1:112
	ds_read2st64_b32 v[48:49], v56 offset0:128 offset1:144
	ds_read2st64_b32 v[50:51], v56 offset0:160 offset1:176
	ds_read2st64_b32 v[52:53], v56 offset0:192 offset1:208
	ds_read2st64_b32 v[54:55], v56 offset0:224 offset1:240
	v_add_u32_e32 v57, 0x10000, v56
	v_add_u32_e32 v58, 0x11000, v56
	v_add_u32_e32 v59, 0x12000, v56
	v_add_u32_e32 v60, 0x13000, v56
	v_add_u32_e32 v61, 0x14000, v56
	v_add_u32_e32 v62, 0x15000, v56
	v_add_u32_e32 v63, 0x16000, v56
	v_add_u32_e32 v56, 0x17000, v56
	ds_read_b32 v57, v57
	ds_read_b32 v58, v58
	ds_read_b32 v59, v59
	ds_read_b32 v60, v60
	ds_read_b32 v61, v61
	ds_read_b32 v62, v62
	ds_read_b32 v63, v63
	ds_read_b32 v56, v56
	s_add_i32 s23, s23, 4
	s_waitcnt vmcnt(7) lgkmcnt(14)
	v_fmac_f32_e32 v12, v72, v40
	v_fmac_f32_e32 v13, v72, v41
	v_fmac_f32_e32 v17, v72, v42
	v_fmac_f32_e32 v18, v72, v43
	s_waitcnt lgkmcnt(13)
	v_fmac_f32_e32 v19, v72, v44
	v_fmac_f32_e32 v20, v72, v45
	s_waitcnt lgkmcnt(12)
	v_fmac_f32_e32 v21, v72, v46
	v_fmac_f32_e32 v22, v72, v47
	s_waitcnt lgkmcnt(11)
	v_fmac_f32_e32 v23, v72, v48
	v_fmac_f32_e32 v24, v72, v49
	s_waitcnt lgkmcnt(10)
	v_fmac_f32_e32 v25, v72, v50
	v_fmac_f32_e32 v26, v72, v51
	s_waitcnt lgkmcnt(9)
	v_fmac_f32_e32 v27, v72, v52
	v_fmac_f32_e32 v28, v72, v53
	s_waitcnt lgkmcnt(8)
	v_fmac_f32_e32 v29, v72, v54
	v_fmac_f32_e32 v30, v72, v55
	s_waitcnt lgkmcnt(7)
	v_fmac_f32_e32 v31, v72, v57
	s_waitcnt lgkmcnt(6)
	v_fmac_f32_e32 v32, v72, v58
	s_waitcnt lgkmcnt(5)
	v_fmac_f32_e32 v33, v72, v59
	s_waitcnt lgkmcnt(4)
	v_fmac_f32_e32 v34, v72, v60
	s_waitcnt lgkmcnt(3)
	v_fmac_f32_e32 v35, v72, v61
	s_waitcnt lgkmcnt(2)
	v_fmac_f32_e32 v36, v72, v62
	s_waitcnt lgkmcnt(1)
	v_fmac_f32_e32 v37, v72, v63
	s_waitcnt lgkmcnt(0)
	v_fmac_f32_e32 v38, v72, v56
	v_add_u32_e32 v56, s23, v3
	ds_read2st64_b32 v[40:41], v56 offset1:16
	ds_read2st64_b32 v[42:43], v56 offset0:32 offset1:48
	ds_read2st64_b32 v[44:45], v56 offset0:64 offset1:80
	ds_read2st64_b32 v[46:47], v56 offset0:96 offset1:112
	ds_read2st64_b32 v[48:49], v56 offset0:128 offset1:144
	ds_read2st64_b32 v[50:51], v56 offset0:160 offset1:176
	ds_read2st64_b32 v[52:53], v56 offset0:192 offset1:208
	ds_read2st64_b32 v[54:55], v56 offset0:224 offset1:240
	v_add_u32_e32 v57, 0x10000, v56
	v_add_u32_e32 v58, 0x11000, v56
	v_add_u32_e32 v59, 0x12000, v56
	v_add_u32_e32 v60, 0x13000, v56
	v_add_u32_e32 v61, 0x14000, v56
	v_add_u32_e32 v62, 0x15000, v56
	v_add_u32_e32 v63, 0x16000, v56
	v_add_u32_e32 v56, 0x17000, v56
	ds_read_b32 v57, v57
	ds_read_b32 v58, v58
	ds_read_b32 v59, v59
	ds_read_b32 v60, v60
	ds_read_b32 v61, v61
	ds_read_b32 v62, v62
	ds_read_b32 v63, v63
	ds_read_b32 v56, v56
	s_add_i32 s23, s23, 4
	s_waitcnt vmcnt(6) lgkmcnt(14)
	v_fmac_f32_e32 v12, v73, v40
	v_fmac_f32_e32 v13, v73, v41
	v_fmac_f32_e32 v17, v73, v42
	v_fmac_f32_e32 v18, v73, v43
	s_waitcnt lgkmcnt(13)
	v_fmac_f32_e32 v19, v73, v44
	v_fmac_f32_e32 v20, v73, v45
	s_waitcnt lgkmcnt(12)
	v_fmac_f32_e32 v21, v73, v46
	v_fmac_f32_e32 v22, v73, v47
	s_waitcnt lgkmcnt(11)
	v_fmac_f32_e32 v23, v73, v48
	v_fmac_f32_e32 v24, v73, v49
	s_waitcnt lgkmcnt(10)
	v_fmac_f32_e32 v25, v73, v50
	v_fmac_f32_e32 v26, v73, v51
	s_waitcnt lgkmcnt(9)
	v_fmac_f32_e32 v27, v73, v52
	v_fmac_f32_e32 v28, v73, v53
	s_waitcnt lgkmcnt(8)
	v_fmac_f32_e32 v29, v73, v54
	v_fmac_f32_e32 v30, v73, v55
	s_waitcnt lgkmcnt(7)
	v_fmac_f32_e32 v31, v73, v57
	s_waitcnt lgkmcnt(6)
	v_fmac_f32_e32 v32, v73, v58
	s_waitcnt lgkmcnt(5)
	v_fmac_f32_e32 v33, v73, v59
	s_waitcnt lgkmcnt(4)
	v_fmac_f32_e32 v34, v73, v60
	s_waitcnt lgkmcnt(3)
	v_fmac_f32_e32 v35, v73, v61
	s_waitcnt lgkmcnt(2)
	v_fmac_f32_e32 v36, v73, v62
	s_waitcnt lgkmcnt(1)
	v_fmac_f32_e32 v37, v73, v63
	s_waitcnt lgkmcnt(0)
	v_fmac_f32_e32 v38, v73, v56
	v_add_u32_e32 v56, s23, v3
	ds_read2st64_b32 v[40:41], v56 offset1:16
	ds_read2st64_b32 v[42:43], v56 offset0:32 offset1:48
	ds_read2st64_b32 v[44:45], v56 offset0:64 offset1:80
	ds_read2st64_b32 v[46:47], v56 offset0:96 offset1:112
	ds_read2st64_b32 v[48:49], v56 offset0:128 offset1:144
	ds_read2st64_b32 v[50:51], v56 offset0:160 offset1:176
	ds_read2st64_b32 v[52:53], v56 offset0:192 offset1:208
	ds_read2st64_b32 v[54:55], v56 offset0:224 offset1:240
	v_add_u32_e32 v57, 0x10000, v56
	v_add_u32_e32 v58, 0x11000, v56
	v_add_u32_e32 v59, 0x12000, v56
	v_add_u32_e32 v60, 0x13000, v56
	v_add_u32_e32 v61, 0x14000, v56
	v_add_u32_e32 v62, 0x15000, v56
	v_add_u32_e32 v63, 0x16000, v56
	v_add_u32_e32 v56, 0x17000, v56
	ds_read_b32 v57, v57
	ds_read_b32 v58, v58
	ds_read_b32 v59, v59
	ds_read_b32 v60, v60
	ds_read_b32 v61, v61
	ds_read_b32 v62, v62
	ds_read_b32 v63, v63
	ds_read_b32 v56, v56
	s_add_i32 s23, s23, 4
	s_waitcnt vmcnt(5) lgkmcnt(14)
	v_fmac_f32_e32 v12, v74, v40
	v_fmac_f32_e32 v13, v74, v41
	v_fmac_f32_e32 v17, v74, v42
	v_fmac_f32_e32 v18, v74, v43
	s_waitcnt lgkmcnt(13)
	v_fmac_f32_e32 v19, v74, v44
	v_fmac_f32_e32 v20, v74, v45
	s_waitcnt lgkmcnt(12)
	v_fmac_f32_e32 v21, v74, v46
	v_fmac_f32_e32 v22, v74, v47
	s_waitcnt lgkmcnt(11)
	v_fmac_f32_e32 v23, v74, v48
	v_fmac_f32_e32 v24, v74, v49
	s_waitcnt lgkmcnt(10)
	v_fmac_f32_e32 v25, v74, v50
	v_fmac_f32_e32 v26, v74, v51
	s_waitcnt lgkmcnt(9)
	v_fmac_f32_e32 v27, v74, v52
	v_fmac_f32_e32 v28, v74, v53
	s_waitcnt lgkmcnt(8)
	v_fmac_f32_e32 v29, v74, v54
	v_fmac_f32_e32 v30, v74, v55
	s_waitcnt lgkmcnt(7)
	v_fmac_f32_e32 v31, v74, v57
	s_waitcnt lgkmcnt(6)
	v_fmac_f32_e32 v32, v74, v58
	s_waitcnt lgkmcnt(5)
	v_fmac_f32_e32 v33, v74, v59
	s_waitcnt lgkmcnt(4)
	v_fmac_f32_e32 v34, v74, v60
	s_waitcnt lgkmcnt(3)
	v_fmac_f32_e32 v35, v74, v61
	s_waitcnt lgkmcnt(2)
	v_fmac_f32_e32 v36, v74, v62
	s_waitcnt lgkmcnt(1)
	v_fmac_f32_e32 v37, v74, v63
	s_waitcnt lgkmcnt(0)
	v_fmac_f32_e32 v38, v74, v56
	v_add_u32_e32 v56, s23, v3
	ds_read2st64_b32 v[40:41], v56 offset1:16
	ds_read2st64_b32 v[42:43], v56 offset0:32 offset1:48
	ds_read2st64_b32 v[44:45], v56 offset0:64 offset1:80
	ds_read2st64_b32 v[46:47], v56 offset0:96 offset1:112
	ds_read2st64_b32 v[48:49], v56 offset0:128 offset1:144
	ds_read2st64_b32 v[50:51], v56 offset0:160 offset1:176
	ds_read2st64_b32 v[52:53], v56 offset0:192 offset1:208
	ds_read2st64_b32 v[54:55], v56 offset0:224 offset1:240
	v_add_u32_e32 v57, 0x10000, v56
	v_add_u32_e32 v58, 0x11000, v56
	v_add_u32_e32 v59, 0x12000, v56
	v_add_u32_e32 v60, 0x13000, v56
	v_add_u32_e32 v61, 0x14000, v56
	v_add_u32_e32 v62, 0x15000, v56
	v_add_u32_e32 v63, 0x16000, v56
	v_add_u32_e32 v56, 0x17000, v56
	ds_read_b32 v57, v57
	ds_read_b32 v58, v58
	ds_read_b32 v59, v59
	ds_read_b32 v60, v60
	ds_read_b32 v61, v61
	ds_read_b32 v62, v62
	ds_read_b32 v63, v63
	ds_read_b32 v56, v56
	s_add_i32 s23, s23, 4
	s_waitcnt vmcnt(4) lgkmcnt(14)
	v_fmac_f32_e32 v12, v75, v40
	v_fmac_f32_e32 v13, v75, v41
	v_fmac_f32_e32 v17, v75, v42
	v_fmac_f32_e32 v18, v75, v43
	s_waitcnt lgkmcnt(13)
	v_fmac_f32_e32 v19, v75, v44
	v_fmac_f32_e32 v20, v75, v45
	s_waitcnt lgkmcnt(12)
	v_fmac_f32_e32 v21, v75, v46
	v_fmac_f32_e32 v22, v75, v47
	s_waitcnt lgkmcnt(11)
	v_fmac_f32_e32 v23, v75, v48
	v_fmac_f32_e32 v24, v75, v49
	s_waitcnt lgkmcnt(10)
	v_fmac_f32_e32 v25, v75, v50
	v_fmac_f32_e32 v26, v75, v51
	s_waitcnt lgkmcnt(9)
	v_fmac_f32_e32 v27, v75, v52
	v_fmac_f32_e32 v28, v75, v53
	s_waitcnt lgkmcnt(8)
	v_fmac_f32_e32 v29, v75, v54
	v_fmac_f32_e32 v30, v75, v55
	s_waitcnt lgkmcnt(7)
	v_fmac_f32_e32 v31, v75, v57
	s_waitcnt lgkmcnt(6)
	v_fmac_f32_e32 v32, v75, v58
	s_waitcnt lgkmcnt(5)
	v_fmac_f32_e32 v33, v75, v59
	s_waitcnt lgkmcnt(4)
	v_fmac_f32_e32 v34, v75, v60
	s_waitcnt lgkmcnt(3)
	v_fmac_f32_e32 v35, v75, v61
	s_waitcnt lgkmcnt(2)
	v_fmac_f32_e32 v36, v75, v62
	s_waitcnt lgkmcnt(1)
	v_fmac_f32_e32 v37, v75, v63
	s_waitcnt lgkmcnt(0)
	v_fmac_f32_e32 v38, v75, v56
	v_add_u32_e32 v56, s23, v3
	ds_read2st64_b32 v[40:41], v56 offset1:16
	ds_read2st64_b32 v[42:43], v56 offset0:32 offset1:48
	ds_read2st64_b32 v[44:45], v56 offset0:64 offset1:80
	ds_read2st64_b32 v[46:47], v56 offset0:96 offset1:112
	ds_read2st64_b32 v[48:49], v56 offset0:128 offset1:144
	ds_read2st64_b32 v[50:51], v56 offset0:160 offset1:176
	ds_read2st64_b32 v[52:53], v56 offset0:192 offset1:208
	ds_read2st64_b32 v[54:55], v56 offset0:224 offset1:240
	v_add_u32_e32 v57, 0x10000, v56
	v_add_u32_e32 v58, 0x11000, v56
	v_add_u32_e32 v59, 0x12000, v56
	v_add_u32_e32 v60, 0x13000, v56
	v_add_u32_e32 v61, 0x14000, v56
	v_add_u32_e32 v62, 0x15000, v56
	v_add_u32_e32 v63, 0x16000, v56
	v_add_u32_e32 v56, 0x17000, v56
	ds_read_b32 v57, v57
	ds_read_b32 v58, v58
	ds_read_b32 v59, v59
	ds_read_b32 v60, v60
	ds_read_b32 v61, v61
	ds_read_b32 v62, v62
	ds_read_b32 v63, v63
	ds_read_b32 v56, v56
	s_add_i32 s23, s23, 4
	s_waitcnt vmcnt(3) lgkmcnt(14)
	v_fmac_f32_e32 v12, v76, v40
	v_fmac_f32_e32 v13, v76, v41
	v_fmac_f32_e32 v17, v76, v42
	v_fmac_f32_e32 v18, v76, v43
	s_waitcnt lgkmcnt(13)
	v_fmac_f32_e32 v19, v76, v44
	v_fmac_f32_e32 v20, v76, v45
	s_waitcnt lgkmcnt(12)
	v_fmac_f32_e32 v21, v76, v46
	v_fmac_f32_e32 v22, v76, v47
	s_waitcnt lgkmcnt(11)
	v_fmac_f32_e32 v23, v76, v48
	v_fmac_f32_e32 v24, v76, v49
	s_waitcnt lgkmcnt(10)
	v_fmac_f32_e32 v25, v76, v50
	v_fmac_f32_e32 v26, v76, v51
	s_waitcnt lgkmcnt(9)
	v_fmac_f32_e32 v27, v76, v52
	v_fmac_f32_e32 v28, v76, v53
	s_waitcnt lgkmcnt(8)
	v_fmac_f32_e32 v29, v76, v54
	v_fmac_f32_e32 v30, v76, v55
	s_waitcnt lgkmcnt(7)
	v_fmac_f32_e32 v31, v76, v57
	s_waitcnt lgkmcnt(6)
	v_fmac_f32_e32 v32, v76, v58
	s_waitcnt lgkmcnt(5)
	v_fmac_f32_e32 v33, v76, v59
	s_waitcnt lgkmcnt(4)
	v_fmac_f32_e32 v34, v76, v60
	s_waitcnt lgkmcnt(3)
	v_fmac_f32_e32 v35, v76, v61
	s_waitcnt lgkmcnt(2)
	v_fmac_f32_e32 v36, v76, v62
	s_waitcnt lgkmcnt(1)
	v_fmac_f32_e32 v37, v76, v63
	s_waitcnt lgkmcnt(0)
	v_fmac_f32_e32 v38, v76, v56
	v_add_u32_e32 v56, s23, v3
	ds_read2st64_b32 v[40:41], v56 offset1:16
	ds_read2st64_b32 v[42:43], v56 offset0:32 offset1:48
	ds_read2st64_b32 v[44:45], v56 offset0:64 offset1:80
	ds_read2st64_b32 v[46:47], v56 offset0:96 offset1:112
	ds_read2st64_b32 v[48:49], v56 offset0:128 offset1:144
	ds_read2st64_b32 v[50:51], v56 offset0:160 offset1:176
	ds_read2st64_b32 v[52:53], v56 offset0:192 offset1:208
	ds_read2st64_b32 v[54:55], v56 offset0:224 offset1:240
	v_add_u32_e32 v57, 0x10000, v56
	v_add_u32_e32 v58, 0x11000, v56
	v_add_u32_e32 v59, 0x12000, v56
	v_add_u32_e32 v60, 0x13000, v56
	v_add_u32_e32 v61, 0x14000, v56
	v_add_u32_e32 v62, 0x15000, v56
	v_add_u32_e32 v63, 0x16000, v56
	v_add_u32_e32 v56, 0x17000, v56
	ds_read_b32 v57, v57
	ds_read_b32 v58, v58
	ds_read_b32 v59, v59
	ds_read_b32 v60, v60
	ds_read_b32 v61, v61
	ds_read_b32 v62, v62
	ds_read_b32 v63, v63
	ds_read_b32 v56, v56
	s_add_i32 s23, s23, 4
	s_waitcnt vmcnt(2) lgkmcnt(14)
	v_fmac_f32_e32 v12, v77, v40
	v_fmac_f32_e32 v13, v77, v41
	v_fmac_f32_e32 v17, v77, v42
	v_fmac_f32_e32 v18, v77, v43
	s_waitcnt lgkmcnt(13)
	v_fmac_f32_e32 v19, v77, v44
	v_fmac_f32_e32 v20, v77, v45
	s_waitcnt lgkmcnt(12)
	v_fmac_f32_e32 v21, v77, v46
	v_fmac_f32_e32 v22, v77, v47
	s_waitcnt lgkmcnt(11)
	v_fmac_f32_e32 v23, v77, v48
	v_fmac_f32_e32 v24, v77, v49
	s_waitcnt lgkmcnt(10)
	v_fmac_f32_e32 v25, v77, v50
	v_fmac_f32_e32 v26, v77, v51
	s_waitcnt lgkmcnt(9)
	v_fmac_f32_e32 v27, v77, v52
	v_fmac_f32_e32 v28, v77, v53
	s_waitcnt lgkmcnt(8)
	v_fmac_f32_e32 v29, v77, v54
	v_fmac_f32_e32 v30, v77, v55
	s_waitcnt lgkmcnt(7)
	v_fmac_f32_e32 v31, v77, v57
	s_waitcnt lgkmcnt(6)
	v_fmac_f32_e32 v32, v77, v58
	s_waitcnt lgkmcnt(5)
	v_fmac_f32_e32 v33, v77, v59
	s_waitcnt lgkmcnt(4)
	v_fmac_f32_e32 v34, v77, v60
	s_waitcnt lgkmcnt(3)
	v_fmac_f32_e32 v35, v77, v61
	s_waitcnt lgkmcnt(2)
	v_fmac_f32_e32 v36, v77, v62
	s_waitcnt lgkmcnt(1)
	v_fmac_f32_e32 v37, v77, v63
	s_waitcnt lgkmcnt(0)
	v_fmac_f32_e32 v38, v77, v56
	v_add_u32_e32 v56, s23, v3
	ds_read2st64_b32 v[40:41], v56 offset1:16
	ds_read2st64_b32 v[42:43], v56 offset0:32 offset1:48
	ds_read2st64_b32 v[44:45], v56 offset0:64 offset1:80
	ds_read2st64_b32 v[46:47], v56 offset0:96 offset1:112
	ds_read2st64_b32 v[48:49], v56 offset0:128 offset1:144
	ds_read2st64_b32 v[50:51], v56 offset0:160 offset1:176
	ds_read2st64_b32 v[52:53], v56 offset0:192 offset1:208
	ds_read2st64_b32 v[54:55], v56 offset0:224 offset1:240
	v_add_u32_e32 v57, 0x10000, v56
	v_add_u32_e32 v58, 0x11000, v56
	v_add_u32_e32 v59, 0x12000, v56
	v_add_u32_e32 v60, 0x13000, v56
	v_add_u32_e32 v61, 0x14000, v56
	v_add_u32_e32 v62, 0x15000, v56
	v_add_u32_e32 v63, 0x16000, v56
	v_add_u32_e32 v56, 0x17000, v56
	ds_read_b32 v57, v57
	ds_read_b32 v58, v58
	ds_read_b32 v59, v59
	ds_read_b32 v60, v60
	ds_read_b32 v61, v61
	ds_read_b32 v62, v62
	ds_read_b32 v63, v63
	ds_read_b32 v56, v56
	s_add_i32 s23, s23, 4
	s_waitcnt vmcnt(1) lgkmcnt(14)
	v_fmac_f32_e32 v12, v78, v40
	v_fmac_f32_e32 v13, v78, v41
	v_fmac_f32_e32 v17, v78, v42
	v_fmac_f32_e32 v18, v78, v43
	s_waitcnt lgkmcnt(13)
	v_fmac_f32_e32 v19, v78, v44
	v_fmac_f32_e32 v20, v78, v45
	s_waitcnt lgkmcnt(12)
	v_fmac_f32_e32 v21, v78, v46
	v_fmac_f32_e32 v22, v78, v47
	s_waitcnt lgkmcnt(11)
	v_fmac_f32_e32 v23, v78, v48
	v_fmac_f32_e32 v24, v78, v49
	s_waitcnt lgkmcnt(10)
	v_fmac_f32_e32 v25, v78, v50
	v_fmac_f32_e32 v26, v78, v51
	s_waitcnt lgkmcnt(9)
	v_fmac_f32_e32 v27, v78, v52
	v_fmac_f32_e32 v28, v78, v53
	s_waitcnt lgkmcnt(8)
	v_fmac_f32_e32 v29, v78, v54
	v_fmac_f32_e32 v30, v78, v55
	s_waitcnt lgkmcnt(7)
	v_fmac_f32_e32 v31, v78, v57
	s_waitcnt lgkmcnt(6)
	v_fmac_f32_e32 v32, v78, v58
	s_waitcnt lgkmcnt(5)
	v_fmac_f32_e32 v33, v78, v59
	s_waitcnt lgkmcnt(4)
	v_fmac_f32_e32 v34, v78, v60
	s_waitcnt lgkmcnt(3)
	v_fmac_f32_e32 v35, v78, v61
	s_waitcnt lgkmcnt(2)
	v_fmac_f32_e32 v36, v78, v62
	s_waitcnt lgkmcnt(1)
	v_fmac_f32_e32 v37, v78, v63
	s_waitcnt lgkmcnt(0)
	v_fmac_f32_e32 v38, v78, v56
	v_add_u32_e32 v56, s23, v3
	ds_read2st64_b32 v[40:41], v56 offset1:16
	ds_read2st64_b32 v[42:43], v56 offset0:32 offset1:48
	ds_read2st64_b32 v[44:45], v56 offset0:64 offset1:80
	ds_read2st64_b32 v[46:47], v56 offset0:96 offset1:112
	ds_read2st64_b32 v[48:49], v56 offset0:128 offset1:144
	ds_read2st64_b32 v[50:51], v56 offset0:160 offset1:176
	ds_read2st64_b32 v[52:53], v56 offset0:192 offset1:208
	ds_read2st64_b32 v[54:55], v56 offset0:224 offset1:240
	v_add_u32_e32 v57, 0x10000, v56
	v_add_u32_e32 v58, 0x11000, v56
	v_add_u32_e32 v59, 0x12000, v56
	v_add_u32_e32 v60, 0x13000, v56
	v_add_u32_e32 v61, 0x14000, v56
	v_add_u32_e32 v62, 0x15000, v56
	v_add_u32_e32 v63, 0x16000, v56
	v_add_u32_e32 v56, 0x17000, v56
	ds_read_b32 v57, v57
	ds_read_b32 v58, v58
	ds_read_b32 v59, v59
	ds_read_b32 v60, v60
	ds_read_b32 v61, v61
	ds_read_b32 v62, v62
	ds_read_b32 v63, v63
	ds_read_b32 v56, v56
	s_add_i32 s23, s23, 4
	s_waitcnt vmcnt(0) lgkmcnt(14)
	v_fmac_f32_e32 v12, v79, v40
	v_fmac_f32_e32 v13, v79, v41
	v_fmac_f32_e32 v17, v79, v42
	v_fmac_f32_e32 v18, v79, v43
	s_waitcnt lgkmcnt(13)
	v_fmac_f32_e32 v19, v79, v44
	v_fmac_f32_e32 v20, v79, v45
	s_waitcnt lgkmcnt(12)
	v_fmac_f32_e32 v21, v79, v46
	v_fmac_f32_e32 v22, v79, v47
	s_waitcnt lgkmcnt(11)
	v_fmac_f32_e32 v23, v79, v48
	v_fmac_f32_e32 v24, v79, v49
	s_waitcnt lgkmcnt(10)
	v_fmac_f32_e32 v25, v79, v50
	v_fmac_f32_e32 v26, v79, v51
	s_waitcnt lgkmcnt(9)
	v_fmac_f32_e32 v27, v79, v52
	v_fmac_f32_e32 v28, v79, v53
	s_waitcnt lgkmcnt(8)
	v_fmac_f32_e32 v29, v79, v54
	v_fmac_f32_e32 v30, v79, v55
	s_waitcnt lgkmcnt(7)
	v_fmac_f32_e32 v31, v79, v57
	s_waitcnt lgkmcnt(6)
	v_fmac_f32_e32 v32, v79, v58
	s_waitcnt lgkmcnt(5)
	v_fmac_f32_e32 v33, v79, v59
	s_waitcnt lgkmcnt(4)
	v_fmac_f32_e32 v34, v79, v60
	s_waitcnt lgkmcnt(3)
	v_fmac_f32_e32 v35, v79, v61
	s_waitcnt lgkmcnt(2)
	v_fmac_f32_e32 v36, v79, v62
	s_waitcnt lgkmcnt(1)
	v_fmac_f32_e32 v37, v79, v63
	s_waitcnt lgkmcnt(0)
	v_fmac_f32_e32 v38, v79, v56
	s_cmpk_eq_i32 s23, 0x200
	s_cbranch_scc0 .LBB0_29
	s_and_b64 s[34:35], s[34:35], exec
	s_cselect_b32 s23, s57, s25
	s_cselect_b32 s34, s56, s24
	ds_write2st64_b32 v16, v12, v13 offset1:1
	ds_write2st64_b32 v16, v17, v18 offset0:2 offset1:3
	ds_write2st64_b32 v16, v19, v20 offset0:4 offset1:5
	ds_write2st64_b32 v16, v21, v22 offset0:6 offset1:7
	ds_write2st64_b32 v16, v23, v24 offset0:8 offset1:9
	ds_write2st64_b32 v16, v25, v26 offset0:10 offset1:11
	ds_write2st64_b32 v16, v27, v28 offset0:12 offset1:13
	ds_write2st64_b32 v16, v29, v30 offset0:14 offset1:15
	ds_write2st64_b32 v16, v31, v32 offset0:16 offset1:17
	ds_write2st64_b32 v16, v33, v34 offset0:18 offset1:19
	ds_write2st64_b32 v16, v35, v36 offset0:20 offset1:21
	ds_write2st64_b32 v16, v37, v38 offset0:22 offset1:23
	v_or_b32_e32 v12, s22, v1
	v_mov_b32_e32 v10, s34
	v_mov_b32_e32 v11, s23
	v_ashrrev_i32_e32 v13, 31, v12
	v_lshl_add_u64 v[10:11], v[12:13], 2, v[10:11]
	v_mad_u64_u32 v[12:13], s[22:23], s92, 24, v[4:5]
	v_mov_b64_e32 v[18:19], s[20:21]
	v_mad_i64_i32 v[12:13], s[20:21], v12, s3, v[18:19]
	v_lshl_add_u64 v[12:13], v[8:9], 0, v[12:13]
	s_mov_b64 s[20:21], 0
	v_mov_b32_e32 v17, v15
	v_mov_b32_e32 v18, v5
	s_waitcnt lgkmcnt(0)
	s_barrier

.LBB0_46:
	s_lshr_b32 s92, s54, 8
	v_cvt_f32_u32_e32 v2, s92
	s_sub_i32 vcc_lo, 0, s92
	s_abs_i32 s96, s97
	s_ashr_i32 s93, s97, 31
	v_rcp_iflag_f32_e32 v2, v2
	v_mov_b32_e32 v15, v11
	v_mov_b32_e32 v17, v11
	v_mul_f32_e32 v2, 0x4f7ffffe, v2
	v_cvt_u32_f32_e32 v2, v2
	s_nop 0
	v_readfirstlane_b32 vcc_hi, v2
	s_mul_i32 vcc_lo, vcc_lo, vcc_hi
	s_mul_hi_u32 vcc_lo, vcc_hi, vcc_lo
	s_add_i32 vcc_hi, vcc_hi, vcc_lo
	s_mul_hi_u32 vcc_lo, s96, vcc_hi
	s_mul_i32 vcc_hi, vcc_lo, s92
	s_sub_i32 s96, s96, vcc_hi
	s_add_i32 vcc_hi, vcc_lo, 1
	s_sub_i32 s6, s96, s92
	s_cmp_ge_u32 s96, s92
	s_cselect_b32 s7, vcc_hi, vcc_lo
	s_cselect_b32 s6, s6, s96
	s_add_i32 s96, s7, 1
	s_cmp_ge_u32 s6, s92
	s_cselect_b32 s6, s96, s7
	s_xor_b32 s6, s6, s93
	s_sub_i32 s6, s6, s93
	s_lshl_b32 s96, s6, 6
	s_mul_i32 s6, s6, s92
	s_sub_i32 s6, s97, s6
	s_lshl_b32 s92, s6, 8
	s_ashr_i32 s93, s92, 31
	s_lshl_b64 vcc, s[92:93], 2
	s_add_u32 s88, s88, vcc_lo
	s_addc_u32 s89, s89, vcc_hi
	v_or_b32_e32 v2, s96, v21
	s_ashr_i32 s97, s96, 31
	v_lshl_add_u64 v[6:7], s[88:89], 0, v[14:15]
	v_mad_u64_u32 v[2:3], s[88:89], v2, s54, 0
	s_mul_i32 s6, s97, s54
	v_add_u32_e32 v3, s6, v3
	v_lshl_add_u64 v[2:3], v[2:3], 2, v[6:7]
	global_load_dwordx4 v[64:67], v[2:3], off
	v_or_b32_e32 v2, s96, v22
	v_mad_u64_u32 v[2:3], s[88:89], v2, s54, 0
	v_add_u32_e32 v3, s6, v3
	v_lshl_add_u64 v[2:3], v[2:3], 2, v[6:7]
	global_load_dwordx4 v[68:71], v[2:3], off
	v_or_b32_e32 v2, s96, v23
	v_mad_u64_u32 v[2:3], s[88:89], v2, s54, 0
	v_add_u32_e32 v3, s6, v3
	v_lshl_add_u64 v[2:3], v[2:3], 2, v[6:7]
	global_load_dwordx4 v[72:75], v[2:3], off
	v_or_b32_e32 v2, s96, v24
	v_mad_u64_u32 v[2:3], s[88:89], v2, s54, 0
	v_add_u32_e32 v3, s6, v3
	v_lshl_add_u64 v[2:3], v[2:3], 2, v[6:7]
	global_load_dwordx4 v[76:79], v[2:3], off
	v_or_b32_e32 v2, s96, v25
	v_mad_u64_u32 v[2:3], s[88:89], v2, s54, 0
	v_add_u32_e32 v3, s6, v3
	v_lshl_add_u64 v[2:3], v[2:3], 2, v[6:7]
	global_load_dwordx4 v[80:83], v[2:3], off
	v_or_b32_e32 v2, s96, v26
	v_mad_u64_u32 v[2:3], s[88:89], v2, s54, 0
	v_add_u32_e32 v3, s6, v3
	v_lshl_add_u64 v[2:3], v[2:3], 2, v[6:7]
	global_load_dwordx4 v[84:87], v[2:3], off
	v_or_b32_e32 v2, s96, v27
	v_mad_u64_u32 v[2:3], s[88:89], v2, s54, 0
	v_add_u32_e32 v3, s6, v3
	v_lshl_add_u64 v[2:3], v[2:3], 2, v[6:7]
	global_load_dwordx4 v[88:91], v[2:3], off
	s_mul_i32 s6, s56, s93
	v_add_u32_e32 v2, s96, v28
	v_ashrrev_i32_e32 v5, 31, v2
	v_mad_u64_u32 v[2:3], s[88:89], v2, s54, 0
	v_mov_b32_e32 v4, v3
	v_mad_u64_u32 v[4:5], s[88:89], v5, s54, v[4:5]
	v_mov_b32_e32 v3, v4
	v_lshl_add_u64 v[2:3], v[2:3], 2, v[6:7]
	global_load_dwordx4 v[92:95], v[2:3], off
	s_lshl_b64 s[88:89], s[96:97], 1
	s_add_u32 s88, s94, s88
	s_addc_u32 s89, s95, s89
	s_waitcnt vmcnt(7)
	ds_write2_b32 v39, v64, v65 offset1:1
	ds_write2_b32 v39, v66, v67 offset0:2 offset1:3
	s_waitcnt vmcnt(6)
	ds_write2_b32 v40, v68, v69 offset1:1
	ds_write2_b32 v40, v70, v71 offset0:2 offset1:3
	s_waitcnt vmcnt(5)
	ds_write2_b32 v41, v72, v73 offset1:1
	ds_write2_b32 v41, v74, v75 offset0:2 offset1:3
	s_waitcnt vmcnt(4)
	ds_write2_b32 v42, v76, v77 offset1:1
	ds_write2_b32 v42, v78, v79 offset0:2 offset1:3
	s_waitcnt vmcnt(3)
	ds_write2_b32 v43, v80, v81 offset1:1
	ds_write2_b32 v44, v82, v83 offset1:1
	s_waitcnt vmcnt(2)
	ds_write2_b32 v45, v84, v85 offset1:1
	ds_write2_b32 v45, v86, v87 offset0:2 offset1:3
	s_waitcnt vmcnt(1)
	ds_write2_b32 v46, v88, v89 offset1:1
	ds_write2_b32 v47, v90, v91 offset1:1
	s_waitcnt vmcnt(0)
	ds_write2_b32 v48, v92, v93 offset1:1
	ds_write2_b32 v48, v94, v95 offset0:2 offset1:3
	s_waitcnt lgkmcnt(0)
	s_barrier
	ds_read_b32 v4, v29
	ds_read_b32 v5, v29 offset:1028
	v_lshl_add_u64 v[2:3], s[88:89], 0, v[16:17]
	s_waitcnt lgkmcnt(0)
	v_cvt_pk_bf16_f32 v4, v4, v5
	ds_read_b32 v5, v29 offset:2056
	ds_read_b32 v6, v29 offset:3084
	s_waitcnt lgkmcnt(0)
	v_cvt_pk_bf16_f32 v5, v5, v6
	ds_read_b32 v6, v29 offset:4112
	ds_read_b32 v7, v29 offset:5140
	s_waitcnt lgkmcnt(0)
	v_cvt_pk_bf16_f32 v6, v6, v7
	ds_read_b32 v7, v29 offset:6168
	ds_read_b32 v8, v29 offset:7196
	s_waitcnt lgkmcnt(0)
	v_cvt_pk_bf16_f32 v7, v7, v8
	v_or_b32_e32 v8, s92, v19
	v_mul_lo_u32 v10, s57, v8
	v_mad_u64_u32 v[8:9], s[88:89], s56, v8, 0
	v_add3_u32 v9, v9, s6, v10
	v_lshl_add_u64 v[8:9], v[8:9], 1, v[2:3]
	global_store_dwordx4 v[8:9], v[4:7], off
	ds_read_b32 v4, v31
	ds_read_b32 v5, v31 offset:1028
	s_waitcnt lgkmcnt(0)
	v_cvt_pk_bf16_f32 v4, v4, v5
	ds_read_b32 v5, v31 offset:2056
	ds_read_b32 v6, v31 offset:3084
	s_waitcnt lgkmcnt(0)
	v_cvt_pk_bf16_f32 v5, v5, v6
	ds_read_b32 v6, v31 offset:4112
	ds_read_b32 v7, v31 offset:5140
	s_waitcnt lgkmcnt(0)
	v_cvt_pk_bf16_f32 v6, v6, v7
	ds_read_b32 v7, v31 offset:6168
	ds_read_b32 v8, v31 offset:7196
	s_waitcnt lgkmcnt(0)
	v_cvt_pk_bf16_f32 v7, v7, v8
	v_or_b32_e32 v8, s92, v30
	v_mul_lo_u32 v10, s57, v8
	v_mad_u64_u32 v[8:9], s[88:89], s56, v8, 0
	v_add3_u32 v9, v9, s6, v10
	v_lshl_add_u64 v[8:9], v[8:9], 1, v[2:3]
	global_store_dwordx4 v[8:9], v[4:7], off
	ds_read_b32 v4, v33
	ds_read_b32 v5, v33 offset:1028
	s_waitcnt lgkmcnt(0)
	v_cvt_pk_bf16_f32 v4, v4, v5
	ds_read_b32 v5, v33 offset:2056
	ds_read_b32 v6, v33 offset:3084
	s_waitcnt lgkmcnt(0)
	v_cvt_pk_bf16_f32 v5, v5, v6
	ds_read_b32 v6, v33 offset:4112
	ds_read_b32 v7, v33 offset:5140
	s_waitcnt lgkmcnt(0)
	v_cvt_pk_bf16_f32 v6, v6, v7
	ds_read_b32 v7, v33 offset:6168
	ds_read_b32 v8, v33 offset:7196
	s_waitcnt lgkmcnt(0)
	v_cvt_pk_bf16_f32 v7, v7, v8
	v_or_b32_e32 v8, s92, v32
	v_mul_lo_u32 v10, s57, v8
	v_mad_u64_u32 v[8:9], s[88:89], s56, v8, 0
	v_add3_u32 v9, v9, s6, v10
	v_lshl_add_u64 v[8:9], v[8:9], 1, v[2:3]
	global_store_dwordx4 v[8:9], v[4:7], off
	ds_read_b32 v4, v35
	ds_read_b32 v5, v35 offset:1028
	s_waitcnt lgkmcnt(0)
	v_cvt_pk_bf16_f32 v4, v4, v5
	ds_read_b32 v5, v35 offset:2056
	ds_read_b32 v6, v35 offset:3084
	s_waitcnt lgkmcnt(0)
	v_cvt_pk_bf16_f32 v5, v5, v6
	ds_read_b32 v6, v35 offset:4112
	ds_read_b32 v7, v35 offset:5140
	s_waitcnt lgkmcnt(0)
	v_cvt_pk_bf16_f32 v6, v6, v7
	ds_read_b32 v7, v35 offset:6168
	ds_read_b32 v8, v35 offset:7196
	s_waitcnt lgkmcnt(0)
	v_cvt_pk_bf16_f32 v7, v7, v8
	v_add_u32_e32 v8, s92, v34
	v_ashrrev_i32_e32 v9, 31, v8
	v_mul_lo_u32 v10, s56, v9
	v_mul_lo_u32 v13, s57, v8
	v_mad_u64_u32 v[8:9], s[56:57], s56, v8, 0
	v_add3_u32 v9, v9, v10, v13
	v_lshl_add_u64 v[2:3], v[8:9], 1, v[2:3]
	global_store_dwordx4 v[2:3], v[4:7], off
	s_barrier
